# v050 with half of each unit's accumulator clear (v[2:65]) done by four v_mfma_f32_32x32x16_bf16 x,Z,Z,0 on the matrix pipe beside 32 v_mov_b64 on the VALU
# speedup vs baseline: 1.0003x; 1.0003x over previous
.LBB0_269:
	s_ashr_i32 s25, s24, 31
	s_lshl_b64 s[26:27], s[24:25], 20
	s_add_u32 s26, s36, s26
	s_addc_u32 s27, s37, s27
	s_and_b64 s[28:29], s[6:7], exec
	s_cselect_b32 s2, s27, s31
	s_cselect_b32 s25, s26, s30
	s_ashr_i32 s23, s22, 31
	s_lshl_b64 s[28:29], s[22:23], 20
	s_add_u32 s28, s38, s28
	s_addc_u32 s29, s39, s29
	s_and_b64 s[34:35], s[6:7], exec
	s_cselect_b32 s23, s29, s57
	s_cselect_b32 s54, s28, s56
	s_ashr_i32 s1, s0, 31
	s_lshl_b64 s[34:35], s[0:1], 13
	s_add_u32 s1, s56, 0x100
	s_addc_u32 s55, s57, 0
	s_add_u32 s8, s30, 0x80080
	s_waitcnt vmcnt(0)
	v_lshl_add_u64 v[66:67], v[168:169], 0, s[34:35]
	s_addc_u32 s9, s31, 0
	s_mov_b32 s56, -2
	v_mov_b64_e32 v[74:75], 0
	v_mov_b64_e32 v[76:77], 0
	v_mov_b64_e32 v[78:79], 0
	v_mov_b64_e32 v[80:81], 0
	v_mov_b64_e32 v[90:91], 0
	v_mov_b64_e32 v[92:93], 0
	v_mov_b64_e32 v[94:95], 0
	v_mov_b64_e32 v[96:97], 0
	v_mfma_f32_32x32x16_bf16 v[2:17], v[74:77], v[74:77], 0
	v_mov_b64_e32 v[98:99], 0
	v_mov_b64_e32 v[100:101], 0
	v_mov_b64_e32 v[102:103], 0
	v_mov_b64_e32 v[104:105], 0
	v_mov_b64_e32 v[106:107], 0
	v_mov_b64_e32 v[108:109], 0
	v_mov_b64_e32 v[110:111], 0
	v_mov_b64_e32 v[112:113], 0
	v_mfma_f32_32x32x16_bf16 v[18:33], v[74:77], v[74:77], 0
	v_mov_b64_e32 v[114:115], 0
	v_mov_b64_e32 v[116:117], 0
	v_mov_b64_e32 v[118:119], 0
	v_mov_b64_e32 v[120:121], 0
	v_mov_b64_e32 v[122:123], 0
	v_mov_b64_e32 v[124:125], 0
	v_mov_b64_e32 v[126:127], 0
	v_mov_b64_e32 v[128:129], 0
	v_mfma_f32_32x32x16_bf16 v[34:49], v[74:77], v[74:77], 0
	v_mov_b64_e32 v[130:131], 0
	v_mov_b64_e32 v[132:133], 0
	v_mov_b64_e32 v[134:135], 0
	v_mov_b64_e32 v[136:137], 0
	v_mov_b64_e32 v[138:139], 0
	v_mov_b64_e32 v[140:141], 0
	v_mov_b64_e32 v[142:143], 0
	v_mov_b64_e32 v[144:145], 0
	v_mfma_f32_32x32x16_bf16 v[50:65], v[74:77], v[74:77], 0
	s_branch .LBB0_271

.LBB0_616:
	s_ashr_i32 s27, s26, 31
	s_lshl_b64 s[28:29], s[26:27], 20
	s_add_u32 s28, s2, s28
	s_addc_u32 s29, s38, s29
	s_and_b64 s[30:31], s[6:7], exec
	s_cselect_b32 s21, s29, s35
	s_cselect_b32 s23, s28, s34
	s_ashr_i32 s25, s24, 31
	s_lshl_b64 s[30:31], s[24:25], 20
	s_add_u32 s30, s39, s30
	s_addc_u32 s31, s40, s31
	s_and_b64 s[36:37], s[6:7], exec
	s_cselect_b32 s25, s31, s9
	s_cselect_b32 s27, s30, s8
	s_add_u32 s61, s8, 0x100
	s_addc_u32 s62, s9, 0
	s_add_u32 s8, s34, 0x80080
	s_addc_u32 s9, s35, 0
	s_mov_b32 s63, -2
	v_mov_b64_e32 v[82:83], 0
	v_mov_b64_e32 v[84:85], 0
	v_mov_b64_e32 v[86:87], 0
	v_mov_b64_e32 v[88:89], 0
	v_mov_b64_e32 v[90:91], 0
	v_mov_b64_e32 v[92:93], 0
	v_mov_b64_e32 v[94:95], 0
	v_mov_b64_e32 v[96:97], 0
	v_mfma_f32_32x32x16_bf16 v[2:17], v[82:85], v[82:85], 0
	v_mov_b64_e32 v[98:99], 0
	v_mov_b64_e32 v[100:101], 0
	v_mov_b64_e32 v[102:103], 0
	v_mov_b64_e32 v[104:105], 0
	v_mov_b64_e32 v[106:107], 0
	v_mov_b64_e32 v[108:109], 0
	v_mov_b64_e32 v[110:111], 0
	v_mov_b64_e32 v[112:113], 0
	v_mfma_f32_32x32x16_bf16 v[18:33], v[82:85], v[82:85], 0
	v_mov_b64_e32 v[114:115], 0
	v_mov_b64_e32 v[116:117], 0
	v_mov_b64_e32 v[118:119], 0
	v_mov_b64_e32 v[120:121], 0
	v_mov_b64_e32 v[122:123], 0
	v_mov_b64_e32 v[124:125], 0
	v_mov_b64_e32 v[126:127], 0
	v_mov_b64_e32 v[128:129], 0
	v_mfma_f32_32x32x16_bf16 v[34:49], v[82:85], v[82:85], 0
	v_mov_b64_e32 v[134:135], 0
	v_mov_b64_e32 v[136:137], 0
	v_mov_b64_e32 v[138:139], 0
	v_mov_b64_e32 v[140:141], 0
	v_mov_b64_e32 v[150:151], 0
	v_mov_b64_e32 v[152:153], 0
	v_mov_b64_e32 v[154:155], 0
	v_mov_b64_e32 v[156:157], 0
	v_mfma_f32_32x32x16_bf16 v[50:65], v[82:85], v[82:85], 0

.LBB0_742:
	s_ashr_i32 s31, s30, 31
	s_lshl_b64 s[12:13], s[30:31], 20
	s_add_u32 s34, s2, s12
	s_addc_u32 s35, s52, s13
	s_and_b64 s[12:13], s[10:11], exec
	s_cselect_b32 s31, s35, s39
	s_cselect_b32 s88, s34, s38
	s_ashr_i32 s29, s28, 31
	s_lshl_b64 s[12:13], s[28:29], 20
	s_add_u32 s36, s53, s12
	s_addc_u32 s37, s54, s13
	s_and_b64 s[12:13], s[10:11], exec
	s_cselect_b32 s29, s37, s45
	s_cselect_b32 s90, s36, s44
	s_ashr_i32 s41, s40, 31
	s_lshl_b64 s[12:13], s[40:41], 13
	s_ashr_i32 s41, s40, 5
	s_lshl_b32 s46, s42, 8
	s_lshl_b32 s42, s42, 7
	s_mul_hi_i32 s50, s41, 0xb000
	s_mul_i32 s41, s41, 0xb000
	s_ashr_i32 s47, s46, 31
	s_ashr_i32 s43, s42, 31
	s_add_u32 s41, s69, s41
	v_lshl_add_u64 v[66:67], v[170:171], 0, s[12:13]
	s_addc_u32 s50, s73, s50
	s_lshl_b64 s[12:13], s[46:47], 2
	s_add_u32 s41, s41, s12
	s_addc_u32 s46, s50, s13
	s_lshl_b64 s[12:13], s[42:43], 2
	s_add_u32 s43, s81, s12
	s_addc_u32 s47, s84, s13
	v_mov_b32_e32 v2, s46
	v_mov_b32_e32 v3, s47
	v_lshl_add_u64 v[70:71], v[172:173], 0, s[12:13]
	s_add_u32 s12, s41, 0x200
	v_cndmask_b32_e64 v69, v2, v3, s[14:15]
	v_mov_b32_e32 v2, s41
	v_mov_b32_e32 v3, s43
	s_addc_u32 s13, s46, 0
	v_cndmask_b32_e64 v68, v2, v3, s[14:15]
	s_add_u32 s41, s44, 0x100
	s_addc_u32 s43, s45, 0
	s_mov_b32 s91, -2
	v_mov_b64_e32 v[90:91], 0
	v_mov_b64_e32 v[92:93], 0
	v_mov_b64_e32 v[94:95], 0
	v_mov_b64_e32 v[96:97], 0
	v_mov_b64_e32 v[98:99], 0
	v_mov_b64_e32 v[100:101], 0
	v_mov_b64_e32 v[102:103], 0
	v_mov_b64_e32 v[104:105], 0
	v_mfma_f32_32x32x16_bf16 v[2:17], v[90:93], v[90:93], 0
	v_mov_b64_e32 v[106:107], 0
	v_mov_b64_e32 v[108:109], 0
	v_mov_b64_e32 v[110:111], 0
	v_mov_b64_e32 v[112:113], 0
	v_mov_b64_e32 v[114:115], 0
	v_mov_b64_e32 v[116:117], 0
	v_mov_b64_e32 v[118:119], 0
	v_mov_b64_e32 v[120:121], 0
	v_mfma_f32_32x32x16_bf16 v[18:33], v[90:93], v[90:93], 0
	v_mov_b64_e32 v[122:123], 0
	v_mov_b64_e32 v[124:125], 0
	v_mov_b64_e32 v[126:127], 0
	v_mov_b64_e32 v[128:129], 0
	v_mov_b64_e32 v[130:131], 0
	v_mov_b64_e32 v[132:133], 0
	v_mov_b64_e32 v[134:135], 0
	v_mov_b64_e32 v[136:137], 0
	v_mfma_f32_32x32x16_bf16 v[34:49], v[90:93], v[90:93], 0
	v_mov_b64_e32 v[138:139], 0
	v_mov_b64_e32 v[140:141], 0
	v_mov_b64_e32 v[142:143], 0
	v_mov_b64_e32 v[144:145], 0
	v_mov_b64_e32 v[146:147], 0
	v_mov_b64_e32 v[148:149], 0
	v_mov_b64_e32 v[150:151], 0
	v_mov_b64_e32 v[152:153], 0
	v_mfma_f32_32x32x16_bf16 v[50:65], v[90:93], v[90:93], 0
	s_branch .LBB0_745

.LBB0_904:
	s_add_u32 s19, s28, 0x100
	s_addc_u32 s21, s29, 0
	s_mov_b32 s60, -2
	v_mov_b64_e32 v[82:83], 0
	v_mov_b64_e32 v[84:85], 0
	v_mov_b64_e32 v[86:87], 0
	v_mov_b64_e32 v[88:89], 0
	v_mov_b64_e32 v[90:91], 0
	v_mov_b64_e32 v[92:93], 0
	v_mov_b64_e32 v[94:95], 0
	v_mov_b64_e32 v[96:97], 0
	v_mfma_f32_32x32x16_bf16 v[2:17], v[82:85], v[82:85], 0
	v_mov_b64_e32 v[98:99], 0
	v_mov_b64_e32 v[100:101], 0
	v_mov_b64_e32 v[102:103], 0
	v_mov_b64_e32 v[104:105], 0
	v_mov_b64_e32 v[106:107], 0
	v_mov_b64_e32 v[108:109], 0
	v_mov_b64_e32 v[110:111], 0
	v_mov_b64_e32 v[112:113], 0
	v_mfma_f32_32x32x16_bf16 v[18:33], v[82:85], v[82:85], 0
	v_mov_b64_e32 v[114:115], 0
	v_mov_b64_e32 v[116:117], 0
	v_mov_b64_e32 v[118:119], 0
	v_mov_b64_e32 v[120:121], 0
	v_mov_b64_e32 v[122:123], 0
	v_mov_b64_e32 v[124:125], 0
	v_mov_b64_e32 v[126:127], 0
	v_mov_b64_e32 v[128:129], 0
	v_mfma_f32_32x32x16_bf16 v[34:49], v[82:85], v[82:85], 0
	v_mov_b64_e32 v[134:135], 0
	v_mov_b64_e32 v[136:137], 0
	v_mov_b64_e32 v[138:139], 0
	v_mov_b64_e32 v[140:141], 0
	v_mov_b64_e32 v[150:151], 0
	v_mov_b64_e32 v[152:153], 0
	v_mov_b64_e32 v[154:155], 0
	v_mov_b64_e32 v[156:157], 0
	v_mfma_f32_32x32x16_bf16 v[50:65], v[82:85], v[82:85], 0
